# FFN gate/up GEMM staging converted to LDS-DMA (global_load_lds_dwordx4, 3 unpadded XOR-swizzled 24KiB stages) on top of XCD tile remap
# speedup vs baseline: 1.0103x; 1.0103x over previous
; DI int tid_l() { int t = threadIdx.x; asm volatile("" : "+v"(t)); return t; }
; DI int bid_l() { int t = blockIdx.x; asm volatile("" : "+s"(t)); return t; }
; template <int MF, int BK, class Epi>
; DI void gemm_phase_t(char* lds, const GemmDesc g, const Epi epi) {
;   constexpr int BM = MF * 64, LS = BK + 8, CPR = BK / 8, RSTEP = 256 / CPR;
;   constexpr int APT = BM * CPR / 256, BPT = 128 * CPR / 256, STG = (BM + 128) * LS, NKK = BK / 16;
;   u16* sbase = (u16*)lds;
;   const int tid = tid_l(), lane = tid & 63, w = tid >> 6, wm = w >> 1, wn = w & 1, l31 = lane & 31, h = lane >> 5;
;   const int ntn = g.Npad / 128, ntm = g.M / BM, ntiles = ntm * ntn, nk = g.K / BK;
;   const int lr = tid / CPR, lc = tid % CPR;
;   for (int t = bid_l(); t < ntiles; t += gridDim.x) {
;     const int tn = t % ntn, tm = t / ntn;
;     const int m0 = tm * BM, n0 = tn * 128;
;     const u16* Ap = g.A + (size_t)(m0 + lr) * g.lda + lc * 8;
;     const u16* Bp = g.Bt + (size_t)(n0 + lr) * g.ldb + lc * 8;
;     u32x4 ra[APT], rb[BPT];
; #pragma unroll
;     for (int j = 0; j < APT; ++j) ra[j] = *(const u32x4*)(Ap + (size_t)j * RSTEP * g.lda);
; #pragma unroll
;     for (int j = 0; j < BPT; ++j) rb[j] = *(const u32x4*)(Bp + (size_t)j * RSTEP * g.ldb);
; #pragma unroll
;     for (int j = 0; j < APT; ++j) *(u32x4*)(sbase + (lr + RSTEP * j) * LS + lc * 8) = ra[j];
; #pragma unroll
;     for (int j = 0; j < BPT; ++j) *(u32x4*)(sbase + BM * LS + (lr + RSTEP * j) * LS + lc * 8) = rb[j];
;     if (nk > 1) {
; #pragma unroll
;       for (int j = 0; j < APT; ++j) ra[j] = *(const u32x4*)(Ap + (size_t)j * RSTEP * g.lda + BK);
; #pragma unroll
;       for (int j = 0; j < BPT; ++j) rb[j] = *(const u32x4*)(Bp + (size_t)j * RSTEP * g.ldb + BK);
;     }
.LBB0_284:
	s_andn2_b64 vcc, exec, s[2:3]
	s_mov_b64 s[2:3], 0
	v_writelane_b32 v253, s2, 39
	s_mov_b64 s[0:1], 0
	s_nop 0
	v_writelane_b32 v253, s3, 40
	s_cbranch_vccnz .LBB0_291
	v_readlane_b32 s2, v253, 41
	s_lshr_b32 s6, s2, 8
	v_mov_b32_e32 v4, v0
	s_mul_i32 s6, s6, 44
	v_readlane_b32 s7, v251, 0
	v_mov_b32_e32 v203, 0x42800000
	v_mov_b32_e32 v208, 0x13004
	v_mov_b32_e32 v214, 0x13000
	v_mov_b32_e32 v177, 0x12090
	s_cmp_ge_i32 s7, s6
	s_cbranch_scc1 .LBB0_290
	v_ashrrev_i32_e32 v2, 31, v4
	v_lshrrev_b32_e32 v2, 30, v2
	s_add_u32 s2, s30, 0x37ac000
	v_add_u32_e32 v5, v4, v2
	s_addc_u32 s3, s31, 0
	v_ashrrev_i32_e32 v2, 2, v5
	v_and_b32_e32 v5, -4, v5
	s_and_b64 s[4:5], s[20:21], exec
	v_sub_u32_e32 v5, v4, v5
	s_cselect_b32 s4, 0, 0x1c364000
	v_lshlrev_b32_e32 v6, 3, v5
	s_add_u32 s4, s30, s4
	v_ashrrev_i32_e32 v7, 31, v6
	s_addc_u32 s5, s31, 0
	v_lshlrev_b64 v[6:7], 1, v[6:7]
	s_waitcnt vmcnt(9)
	v_bfe_u32 v8, v0, 4, 2
	v_lshlrev_b32_e32 v8, 4, v8
	v_lshl_add_u64 v[160:161], s[4:5], 0, v[6:7]
	v_xor_b32_e32 v160, v160, v8
	s_mov_b64 s[4:5], 0x164c000
	v_and_b32_e32 v170, 64, v4
	v_lshl_add_u64 v[156:157], s[30:31], 0, v[6:7]
	v_xor_b32_e32 v156, v156, v8
	s_waitcnt vmcnt(8)
	v_lshl_add_u64 v[162:163], v[160:161], 0, s[4:5]
	v_and_b32_e32 v6, 0x5f, v4
	v_lshrrev_b32_e32 v7, 1, v4
	v_and_b32_e32 v172, 0xffffff9f, v4
	v_or_b32_e32 v4, 0x60, v4
	s_movk_i32 s4, 0x50
	s_mov_b64 s[8:9], 0x147ac000
	v_lshlrev_b32_e32 v5, 4, v5
	v_and_b32_e32 v171, 16, v7
	v_mul_lo_u32 v4, v4, s4
	v_mul_lo_u32 v7, v2, s4
	v_mul_lo_u32 v8, v172, s4
	v_mul_u32_u24_e32 v6, 0x50, v6
	v_lshl_add_u64 v[158:159], v[156:157], 0, s[8:9]
	v_bfe_u32 v4, v0, 2, 2
	v_lshlrev_b32_e32 v4, 4, v4
	v_xor_b32_e32 v4, v4, v171
	v_lshrrev_b32_e32 v5, 6, v0
	v_lshlrev_b32_e32 v5, 10, v5
	v_sub_u32_e32 v4, v4, v5
	v_lshl_add_u32 v175, v172, 6, v4
	v_xor_b32_e32 v176, 32, v175
	v_and_b32_e32 v6, 0x5f, v0
	v_lshl_add_u32 v174, v6, 6, v4
	v_add_u32_e32 v174, 0x4000, v174
	v_xor_b32_e32 v173, 32, v174
	v_readfirstlane_b32 s98, v5
	s_add_u32 s98, s98, 0x100
	s_add_u32 s99, s98, 0x6000
	s_add_u32 s100, s98, 0xc000
.LBB0_287:
	s_mul_hi_i32 s4, s7, 0x2e8ba2e9
	s_lshr_b32 s5, s4, 31
	s_ashr_i32 s4, s4, 3
	s_add_i32 s4, s4, s5
	s_lshl_b32 s8, s4, 8
	v_add_u32_e32 v4, s8, v2
	s_mul_i32 s5, s4, 44
	v_ashrrev_i32_e32 v5, 31, v4
	s_sub_i32 s5, s7, s5
	v_lshlrev_b64 v[68:69], 11, v[4:5]
	s_lshl_b32 s9, s5, 7
	v_lshl_add_u64 v[70:71], v[158:159], 0, v[68:69]
	s_mov_b32 s5, 0x20000
	v_add_co_u32_e32 v74, vcc, s5, v70
	s_mov_b32 s4, 0x40000
	s_nop 0
	v_addc_co_u32_e32 v75, vcc, 0, v71, vcc
	v_add_u32_e32 v4, s9, v2
	v_add_co_u32_e32 v76, vcc, s4, v70
	v_ashrrev_i32_e32 v5, 31, v4
	s_nop 0
	v_addc_co_u32_e32 v77, vcc, 0, v71, vcc
	s_mov_b32 s4, 0x60000
	v_lshlrev_b64 v[72:73], 11, v[4:5]
	v_add_co_u32_e32 v78, vcc, s4, v70
	v_lshl_add_u64 v[80:81], v[162:163], 0, v[72:73]
	s_nop 0
	v_addc_co_u32_e32 v79, vcc, 0, v71, vcc
	v_add_co_u32_e32 v82, vcc, s5, v80
	s_mov_b32 m0, s98
	s_nop 0
	global_load_lds_dwordx4 v[70:71], off
	s_add_i32 m0, s98, 0x1000
	s_nop 0
	global_load_lds_dwordx4 v[74:75], off
	v_addc_co_u32_e32 v83, vcc, 0, v81, vcc
	s_add_i32 m0, s98, 0x2000
	s_nop 0
	global_load_lds_dwordx4 v[76:77], off
	s_add_i32 m0, s98, 0x3000
	s_nop 0
	global_load_lds_dwordx4 v[78:79], off
	s_add_i32 m0, s98, 0x4000
	s_nop 0
	global_load_lds_dwordx4 v[80:81], off
	s_add_i32 m0, s98, 0x5000
	s_nop 0
	global_load_lds_dwordx4 v[82:83], off
	s_add_i32 m0, s99, 0xffffffc0
	s_nop 0
	global_load_lds_dwordx4 v[70:71], off offset:64
	s_add_i32 m0, s99, 0xfc0
	s_nop 0
	global_load_lds_dwordx4 v[74:75], off offset:64
	s_add_i32 m0, s99, 0x1fc0
	s_nop 0
	global_load_lds_dwordx4 v[76:77], off offset:64
	s_add_i32 m0, s99, 0x2fc0
	s_nop 0
	global_load_lds_dwordx4 v[78:79], off offset:64
	s_add_i32 m0, s99, 0x3fc0
	s_nop 0
	global_load_lds_dwordx4 v[80:81], off offset:64
	s_add_i32 m0, s99, 0x4fc0
	s_nop 0
	global_load_lds_dwordx4 v[82:83], off offset:64
	v_mov_b32_e32 v4, 0
	s_mov_b64 s[4:5], 0
	v_mov_b32_e32 v5, v4
	v_mov_b32_e32 v6, v4
	v_mov_b32_e32 v7, v4
	v_mov_b32_e32 v8, v4
	v_mov_b32_e32 v9, v4
	v_mov_b32_e32 v10, v4
	v_mov_b32_e32 v11, v4
	v_mov_b32_e32 v12, v4
	v_mov_b32_e32 v13, v4
	v_mov_b32_e32 v14, v4
	v_mov_b32_e32 v15, v4
	v_mov_b32_e32 v16, v4
	v_mov_b32_e32 v17, v4
	v_mov_b32_e32 v18, v4
	v_mov_b32_e32 v19, v4
	v_mov_b32_e32 v20, v4
	v_mov_b32_e32 v21, v4
	v_mov_b32_e32 v22, v4
	v_mov_b32_e32 v23, v4
	v_mov_b32_e32 v24, v4
	v_mov_b32_e32 v25, v4
	v_mov_b32_e32 v26, v4
	v_mov_b32_e32 v27, v4
	v_mov_b32_e32 v28, v4
	v_mov_b32_e32 v29, v4
	v_mov_b32_e32 v30, v4
	v_mov_b32_e32 v31, v4
	v_mov_b32_e32 v32, v4
	v_mov_b32_e32 v33, v4
	v_mov_b32_e32 v34, v4
	v_mov_b32_e32 v35, v4
	v_mov_b32_e32 v36, v4
	v_mov_b32_e32 v37, v4
	v_mov_b32_e32 v38, v4
	v_mov_b32_e32 v39, v4
	v_mov_b32_e32 v40, v4
	v_mov_b32_e32 v41, v4
	v_mov_b32_e32 v42, v4
	v_lshl_add_u64 v[164:165], v[156:157], 0, v[68:69]
	v_lshl_add_u64 v[168:169], v[160:161], 0, v[72:73]
	v_mov_b32_e32 v43, v4
	v_mov_b32_e32 v68, v4
	v_mov_b32_e32 v69, v4
	v_mov_b32_e32 v70, v4
	v_mov_b32_e32 v71, v4
	v_mov_b32_e32 v72, v4
	v_mov_b32_e32 v44, v4
	v_mov_b32_e32 v45, v4
	v_mov_b32_e32 v46, v4
	v_mov_b32_e32 v47, v4
	v_mov_b32_e32 v48, v4
	v_mov_b32_e32 v49, v4
	v_mov_b32_e32 v50, v4
	v_mov_b32_e32 v51, v4
	v_mov_b32_e32 v52, v4
	v_mov_b32_e32 v53, v4
	v_mov_b32_e32 v54, v4
	v_mov_b32_e32 v55, v4
	v_mov_b32_e32 v56, v4
	v_mov_b32_e32 v57, v4
	v_mov_b32_e32 v58, v4
	v_mov_b32_e32 v59, v4
	v_mov_b32_e32 v60, v4
	v_mov_b32_e32 v61, v4
	v_mov_b32_e32 v62, v4
	v_mov_b32_e32 v63, v4
	v_mov_b32_e32 v64, v4
	v_mov_b32_e32 v65, v4
	v_mov_b32_e32 v66, v4
	v_mov_b32_e32 v67, v4
; template <int MF, int BK, class Epi>
; DI void gemm_phase_t(char* lds, const GemmDesc g, const Epi epi) {
;     ...
;     for (int kt = 0; kt < nk; ++kt) {
;       __syncthreads();
;       const u16* sA = sbase + (kt & 1) * STG;
;       const u16* sB = sA + BM * LS;
;       if (kt + 1 < nk) {
;         u16* nA = sbase + ((kt + 1) & 1) * STG;
; #pragma unroll
;         for (int j = 0; j < APT; ++j) *(u32x4*)(nA + (lr + RSTEP * j) * LS + lc * 8) = ra[j];
; #pragma unroll
;         for (int j = 0; j < BPT; ++j) *(u32x4*)(nA + BM * LS + (lr + RSTEP * j) * LS + lc * 8) = rb[j];
;         if (kt + 2 < nk) {
; #pragma unroll
;           for (int j = 0; j < APT; ++j) ra[j] = *(const u32x4*)(Ap + (size_t)j * RSTEP * g.lda + (kt + 2) * BK);
; #pragma unroll
;           for (int j = 0; j < BPT; ++j) rb[j] = *(const u32x4*)(Bp + (size_t)j * RSTEP * g.ldb + (kt + 2) * BK);
;         }
;       }
;       bf16x8 af[NKK][MF], bfr[NKK][2];
; #pragma unroll
;       for (int kk = 0; kk < NKK; ++kk) {
; #pragma unroll
;         for (int ni = 0; ni < 2; ++ni) bfr[kk][ni] = *(const bf16x8*)(sB + (wn * 64 + ni * 32 + l31) * LS + kk * 16 + h * 8);
; #pragma unroll
;         for (int mi = 0; mi < MF; ++mi) af[kk][mi] = *(const bf16x8*)(sA + (wm * (MF * 32) + mi * 32 + l31) * LS + kk * 16 + h * 8);
;       }
	v_mov_b32_e32 v73, v4
	v_mov_b32_e32 v74, v4
	v_mov_b32_e32 v75, v4
	v_mov_b32_e32 v76, v4
	v_mov_b32_e32 v77, v4
	v_mov_b32_e32 v78, v4
	v_mov_b32_e32 v79, v4
	v_mov_b32_e32 v80, v4
	v_mov_b32_e32 v81, v4
	v_mov_b32_e32 v82, v4
	v_mov_b32_e32 v83, v4
	v_mov_b32_e32 v84, v4
	v_mov_b32_e32 v85, v4
	v_mov_b32_e32 v86, v4
	v_mov_b32_e32 v87, v4
	v_mov_b32_e32 v88, v4
	v_mov_b32_e32 v89, v4
	v_mov_b32_e32 v90, v4
	v_mov_b32_e32 v91, v4
	v_mov_b32_e32 v92, v4
	v_mov_b32_e32 v93, v4
	v_mov_b32_e32 v94, v4
	v_mov_b32_e32 v95, v4
	v_mov_b32_e32 v96, v4
	v_mov_b32_e32 v97, v4
	v_mov_b32_e32 v98, v4
	v_mov_b32_e32 v99, v4
	v_mov_b32_e32 v100, v4
	v_mov_b32_e32 v101, v4
	v_mov_b32_e32 v102, v4
	v_mov_b32_e32 v103, v4
	v_mov_b32_e32 v104, v4
	v_mov_b32_e32 v105, v4
	v_mov_b32_e32 v106, v4
	v_mov_b32_e32 v107, v4
	v_mov_b32_e32 v108, v4
	v_mov_b32_e32 v109, v4
	v_mov_b32_e32 v110, v4
	v_mov_b32_e32 v111, v4
	v_mov_b32_e32 v112, v4
	v_mov_b32_e32 v113, v4
	v_mov_b32_e32 v114, v4
	v_mov_b32_e32 v115, v4
	v_mov_b32_e32 v116, v4
	v_mov_b32_e32 v117, v4
	v_mov_b32_e32 v118, v4
	v_mov_b32_e32 v119, v4
	v_mov_b32_e32 v120, v4
	v_mov_b32_e32 v121, v4
	v_mov_b32_e32 v122, v4
	v_mov_b32_e32 v123, v4
	v_mov_b32_e32 v124, v4
	v_mov_b32_e32 v125, v4
	v_mov_b32_e32 v126, v4
	v_mov_b32_e32 v127, v4
	v_mov_b32_e32 v128, v4
	v_mov_b32_e32 v129, v4
	v_mov_b32_e32 v130, v4
	v_mov_b32_e32 v131, v4
	s_mov_b32 s11, 0x147ac000
	s_mov_b32 s12, 0x147cc000
	s_mov_b32 s13, 0x147ec000
	s_mov_b32 s14, 0x1480c000
.LBB0_288:
	v_lshl_add_u64 v[186:187], v[164:165], 0, s[4:5]
	v_add_co_u32_e32 v194, vcc, s11, v186
	v_lshl_add_u64 v[204:205], v[168:169], 0, s[4:5]
	s_nop 0
	v_addc_co_u32_e32 v195, vcc, 0, v187, vcc
	v_add_co_u32_e32 v198, vcc, s12, v186
	s_mov_b32 s10, 0x164c000
	s_nop 0
	v_addc_co_u32_e32 v199, vcc, 0, v187, vcc
	v_add_co_u32_e32 v200, vcc, s13, v186
	s_waitcnt lgkmcnt(0)
	s_nop 0
	v_addc_co_u32_e32 v201, vcc, 0, v187, vcc
	v_add_co_u32_e32 v246, vcc, s14, v186
	s_waitcnt vmcnt(6)
	s_barrier
	s_nop 0
	v_addc_co_u32_e32 v247, vcc, 0, v187, vcc
	v_add_co_u32_e32 v248, vcc, s10, v204
	s_mov_b32 s10, 0x166c000
	s_nop 0
	v_addc_co_u32_e32 v249, vcc, 0, v205, vcc
	v_add_co_u32_e32 v216, vcc, s10, v204
	s_add_i32 m0, s100, 0xffffff80
	s_nop 0
	global_load_lds_dwordx4 v[194:195], off offset:128
	s_add_i32 m0, s100, 0xf80
	s_nop 0
	global_load_lds_dwordx4 v[198:199], off offset:128
	s_add_i32 m0, s100, 0x1f80
	s_nop 0
	global_load_lds_dwordx4 v[200:201], off offset:128
	s_add_i32 m0, s100, 0x2f80
	s_nop 0
	global_load_lds_dwordx4 v[246:247], off offset:128
	v_addc_co_u32_e32 v217, vcc, 0, v205, vcc
	s_add_i32 m0, s100, 0x3f80
	s_nop 0
	global_load_lds_dwordx4 v[248:249], off offset:128
	s_add_i32 m0, s100, 0x4f80
	s_nop 0
	global_load_lds_dwordx4 v[216:217], off offset:128
	v_add_u32_e32 v178, s98, v175
	v_add_u32_e32 v179, s98, v176
	v_add_u32_e32 v180, s98, v174
	v_add_u32_e32 v181, s98, v173
	ds_read_b128 v[132:135], v180
	ds_read_b128 v[222:225], v181
	ds_read_b128 v[136:139], v180 offset:2048
	ds_read_b128 v[226:229], v181 offset:2048
	ds_read_b128 v[140:143], v178
	ds_read_b128 v[144:147], v179
	ds_read_b128 v[148:151], v178 offset:2048
	ds_read_b128 v[152:155], v179 offset:2048
	ds_read_b128 v[230:233], v178 offset:4096
	ds_read_b128 v[234:237], v179 offset:4096
	ds_read_b128 v[238:241], v178 offset:6144
	ds_read_b128 v[242:245], v179 offset:6144
	s_waitcnt lgkmcnt(7)
	v_mfma_f32_32x32x16_bf16 v[116:131], v[132:135], v[140:143], v[116:131]
	s_waitcnt lgkmcnt(0)
	s_waitcnt vmcnt(6)
	s_barrier
	v_mfma_f32_32x32x16_bf16 v[100:115], v[136:139], v[140:143], v[100:115]
	v_mfma_f32_32x32x16_bf16 v[84:99], v[132:135], v[148:151], v[84:99]
	v_mfma_f32_32x32x16_bf16 v[68:83], v[136:139], v[148:151], v[68:83]
	v_mfma_f32_32x32x16_bf16 v[52:67], v[132:135], v[230:233], v[52:67]
	v_mfma_f32_32x32x16_bf16 v[36:51], v[136:139], v[230:233], v[36:51]
	v_mfma_f32_32x32x16_bf16 v[20:35], v[132:135], v[238:241], v[20:35]
	v_mfma_f32_32x32x16_bf16 v[4:19], v[136:139], v[238:241], v[4:19]
	s_add_i32 m0, s98, 0xffffff40
	s_nop 0
	global_load_lds_dwordx4 v[194:195], off offset:192
	s_add_i32 m0, s98, 0xf40
	s_nop 0
	global_load_lds_dwordx4 v[198:199], off offset:192
	v_mfma_f32_32x32x16_bf16 v[116:131], v[222:225], v[144:147], v[116:131]
	v_mfma_f32_32x32x16_bf16 v[100:115], v[226:229], v[144:147], v[100:115]
	v_mfma_f32_32x32x16_bf16 v[84:99], v[222:225], v[152:155], v[84:99]
	v_mfma_f32_32x32x16_bf16 v[68:83], v[226:229], v[152:155], v[68:83]
	s_add_i32 m0, s98, 0x1f40
	s_nop 0
	global_load_lds_dwordx4 v[200:201], off offset:192
	s_add_i32 m0, s98, 0x2f40
	s_nop 0
	global_load_lds_dwordx4 v[246:247], off offset:192
	s_add_i32 m0, s98, 0x3f40
	s_nop 0
	global_load_lds_dwordx4 v[248:249], off offset:192
	s_add_i32 m0, s98, 0x4f40
	s_nop 0
	global_load_lds_dwordx4 v[216:217], off offset:192
	v_add_u32_e32 v132, s99, v175
	v_add_u32_e32 v133, s99, v176
	v_add_u32_e32 v134, s99, v174
	v_add_u32_e32 v135, s99, v173
	ds_read_b128 v[178:181], v134
	ds_read_b128 v[182:185], v135
	ds_read_b128 v[186:189], v134 offset:2048
	ds_read_b128 v[190:193], v135 offset:2048
	v_mfma_f32_32x32x16_bf16 v[52:67], v[222:225], v[234:237], v[52:67]
	v_mfma_f32_32x32x16_bf16 v[36:51], v[226:229], v[234:237], v[36:51]
	v_mfma_f32_32x32x16_bf16 v[20:35], v[222:225], v[242:245], v[20:35]
	ds_read_b128 v[204:207], v132
	ds_read_b128 v[218:221], v133
	ds_read_b128 v[222:225], v132 offset:2048
	ds_read_b128 v[230:233], v133 offset:2048
	ds_read_b128 v[234:237], v132 offset:4096
	ds_read_b128 v[238:241], v133 offset:4096
	ds_read_b128 v[246:249], v132 offset:6144
	ds_read_b128 v[198:201], v133 offset:6144
	v_mfma_f32_32x32x16_bf16 v[4:19], v[226:229], v[242:245], v[4:19]
	s_waitcnt lgkmcnt(7)
; #define MFMA32(a, b, c) __builtin_amdgcn_mfma_f32_32x32x16_bf16((a), (b), (c), 0, 0, 0)
; DI unsigned pack2(float a, float b) { f2_t v = {a, b}; return __builtin_bit_cast(unsigned, __builtin_convertvector(v, bf2_t)); }
; template <int MF, int BK, class Epi>
; DI void gemm_phase_t(char* lds, const GemmDesc g, const Epi epi) {
;     ...
;     for (int kt = 0; kt < nk; ++kt) {
;       __syncthreads();
;       const u16* sA = sbase + (kt & 1) * STG;
;       const u16* sB = sA + BM * LS;
;       if (kt + 1 < nk) {
;         u16* nA = sbase + ((kt + 1) & 1) * STG;
; #pragma unroll
;         for (int j = 0; j < APT; ++j) *(u32x4*)(nA + (lr + RSTEP * j) * LS + lc * 8) = ra[j];
; #pragma unroll
;         for (int j = 0; j < BPT; ++j) *(u32x4*)(nA + BM * LS + (lr + RSTEP * j) * LS + lc * 8) = rb[j];
;         if (kt + 2 < nk) {
; #pragma unroll
;           for (int j = 0; j < APT; ++j) ra[j] = *(const u32x4*)(Ap + (size_t)j * RSTEP * g.lda + (kt + 2) * BK);
; #pragma unroll
;           for (int j = 0; j < BPT; ++j) rb[j] = *(const u32x4*)(Bp + (size_t)j * RSTEP * g.ldb + (kt + 2) * BK);
;         }
;       }
;       bf16x8 af[NKK][MF], bfr[NKK][2];
; #pragma unroll
;       for (int kk = 0; kk < NKK; ++kk) {
; #pragma unroll
;         for (int ni = 0; ni < 2; ++ni) bfr[kk][ni] = *(const bf16x8*)(sB + (wn * 64 + ni * 32 + l31) * LS + kk * 16 + h * 8);
; #pragma unroll
;         for (int mi = 0; mi < MF; ++mi) af[kk][mi] = *(const bf16x8*)(sA + (wm * (MF * 32) + mi * 32 + l31) * LS + kk * 16 + h * 8);
;       }
;       __builtin_amdgcn_sched_barrier(0);
; #pragma unroll
;       for (int kk = 0; kk < NKK; ++kk)
; #pragma unroll
;         for (int mi = 0; mi < MF; ++mi)
; #pragma unroll
;           for (int ni = 0; ni < 2; ++ni) acc[mi][ni] = MFMA32(bfr[kk][ni], af[kk][mi], acc[mi][ni]);
;   template <int MF> DI void operator()(f32x16 (&acc)[MF][2], int mb, int nb, int l31, int h) const {
; #pragma unroll
;     for (int mi = 0; mi < MF; ++mi) {
;       const int row = mb + mi * 32 + l31;
; #pragma unroll
;       for (int gp = 0; gp < 2; ++gp) {
;         const int j0 = (nb >> 1) + 16 * h + 8 * gp;
;         float v[8];
; #pragma unroll
;         for (int i = 0; i < 8; ++i) v[i] = siluf(acc[mi][0][8 * gp + i]) * acc[mi][1][8 * gp + i];
;         *(u32x4*)(act + (size_t)row * FF + j0) = (u32x4){pack2(v[0], v[1]), pack2(v[2], v[3]), pack2(v[4], v[5]), pack2(v[6], v[7])};
;       }
	v_mfma_f32_32x32x16_bf16 v[116:131], v[178:181], v[204:207], v[116:131]
	s_add_u32 s4, s4, 0x80
	s_addc_u32 s5, s5, 0
	s_cmpk_eq_i32 s4, 0x780
	v_mfma_f32_32x32x16_bf16 v[100:115], v[186:189], v[204:207], v[100:115]
	s_waitcnt lgkmcnt(5)
	v_mfma_f32_32x32x16_bf16 v[84:99], v[178:181], v[222:225], v[84:99]
	v_mfma_f32_32x32x16_bf16 v[68:83], v[186:189], v[222:225], v[68:83]
	s_waitcnt lgkmcnt(3)
	v_mfma_f32_32x32x16_bf16 v[52:67], v[178:181], v[234:237], v[52:67]
	v_mfma_f32_32x32x16_bf16 v[36:51], v[186:189], v[234:237], v[36:51]
	s_waitcnt lgkmcnt(1)
	v_mfma_f32_32x32x16_bf16 v[20:35], v[178:181], v[246:249], v[20:35]
	v_mfma_f32_32x32x16_bf16 v[4:19], v[186:189], v[246:249], v[4:19]
	v_mfma_f32_32x32x16_bf16 v[116:131], v[182:185], v[218:221], v[116:131]
	v_mfma_f32_32x32x16_bf16 v[100:115], v[190:193], v[218:221], v[100:115]
	v_mfma_f32_32x32x16_bf16 v[84:99], v[182:185], v[230:233], v[84:99]
	v_mfma_f32_32x32x16_bf16 v[68:83], v[190:193], v[230:233], v[68:83]
	v_mfma_f32_32x32x16_bf16 v[52:67], v[182:185], v[238:241], v[52:67]
	v_mfma_f32_32x32x16_bf16 v[36:51], v[190:193], v[238:241], v[36:51]
	s_waitcnt lgkmcnt(0)
	v_mfma_f32_32x32x16_bf16 v[20:35], v[182:185], v[198:201], v[20:35]
	v_mfma_f32_32x32x16_bf16 v[4:19], v[190:193], v[198:201], v[4:19]
	s_mov_b32 s101, s100
	s_mov_b32 s100, s99
	s_mov_b32 s99, s98
	s_mov_b32 s98, s101
	s_cbranch_scc0 .LBB0_288
	s_waitcnt vmcnt(6)
	s_barrier
	v_add_u32_e32 v222, s98, v175
	v_add_u32_e32 v223, s98, v176
	v_add_u32_e32 v224, s98, v174
	v_add_u32_e32 v225, s98, v173
	ds_read_b128 v[132:135], v224
	ds_read_b128 v[136:139], v225
	ds_read_b128 v[140:143], v224 offset:2048
	ds_read_b128 v[144:147], v225 offset:2048
	ds_read_b128 v[148:151], v222
	ds_read_b128 v[152:155], v223
	ds_read_b128 v[178:181], v222 offset:2048
	ds_read_b128 v[182:185], v223 offset:2048
	ds_read_b128 v[186:189], v222 offset:4096
	ds_read_b128 v[190:193], v223 offset:4096
	ds_read_b128 v[204:207], v222 offset:6144
	ds_read_b128 v[218:221], v223 offset:6144
	s_waitcnt lgkmcnt(7)
	v_mfma_f32_32x32x16_bf16 v[116:131], v[132:135], v[148:151], v[116:131]
	s_waitcnt lgkmcnt(0)
	s_waitcnt vmcnt(0)
	s_barrier
	v_mfma_f32_32x32x16_bf16 v[100:115], v[140:143], v[148:151], v[100:115]
	v_mfma_f32_32x32x16_bf16 v[84:99], v[132:135], v[178:181], v[84:99]
	v_mfma_f32_32x32x16_bf16 v[68:83], v[140:143], v[178:181], v[68:83]
	v_mfma_f32_32x32x16_bf16 v[52:67], v[132:135], v[186:189], v[52:67]
	v_mfma_f32_32x32x16_bf16 v[36:51], v[140:143], v[186:189], v[36:51]
	v_mfma_f32_32x32x16_bf16 v[20:35], v[132:135], v[204:207], v[20:35]
	v_mfma_f32_32x32x16_bf16 v[4:19], v[140:143], v[204:207], v[4:19]
	v_mfma_f32_32x32x16_bf16 v[116:131], v[136:139], v[152:155], v[116:131]
	v_mfma_f32_32x32x16_bf16 v[100:115], v[144:147], v[152:155], v[100:115]
	v_mfma_f32_32x32x16_bf16 v[84:99], v[136:139], v[182:185], v[84:99]
	v_mfma_f32_32x32x16_bf16 v[68:83], v[144:147], v[182:185], v[68:83]
	v_mfma_f32_32x32x16_bf16 v[52:67], v[136:139], v[190:193], v[52:67]
	v_mfma_f32_32x32x16_bf16 v[36:51], v[144:147], v[190:193], v[36:51]
	v_mfma_f32_32x32x16_bf16 v[20:35], v[136:139], v[218:221], v[20:35]
	v_mfma_f32_32x32x16_bf16 v[4:19], v[144:147], v[218:221], v[4:19]
	v_add_u32_e32 v226, s99, v175
	v_add_u32_e32 v227, s99, v176
	v_add_u32_e32 v228, s99, v174
	v_add_u32_e32 v229, s99, v173
	s_mov_b32 s101, s100
	s_mov_b32 s100, s99
	s_mov_b32 s99, s98
	s_mov_b32 s98, s101
	ds_read_b128 v[132:135], v226 offset:6144
	ds_read_b128 v[136:139], v227 offset:6144
	ds_read_b128 v[140:143], v227 offset:4096
	ds_read_b128 v[144:147], v227 offset:2048
	ds_read_b128 v[148:151], v226
	ds_read_b128 v[152:155], v227
	ds_read_b128 v[178:181], v229 offset:2048
	ds_read_b128 v[182:185], v228
	ds_read_b128 v[186:189], v229
	ds_read_b128 v[190:193], v226 offset:4096
	ds_read_b128 v[204:207], v226 offset:2048
	ds_read_b128 v[218:221], v228 offset:2048
	s_waitcnt lgkmcnt(4)
	v_mfma_f32_32x32x16_bf16 v[116:131], v[182:185], v[148:151], v[116:131]
	s_waitcnt lgkmcnt(3)
	v_mfma_f32_32x32x16_bf16 v[116:131], v[186:189], v[152:155], v[116:131]
	s_waitcnt lgkmcnt(2)
	v_mfma_f32_32x32x16_bf16 v[52:67], v[182:185], v[190:193], v[52:67]
	s_waitcnt lgkmcnt(0)
	v_mfma_f32_32x32x16_bf16 v[36:51], v[218:221], v[190:193], v[36:51]
	v_mfma_f32_32x32x16_bf16 v[20:35], v[182:185], v[132:135], v[20:35]
	v_mfma_f32_32x32x16_bf16 v[4:19], v[218:221], v[132:135], v[4:19]
	s_nop 5
	v_mul_f32_e32 v135, 0xbfb8aa3b, v116
	v_exp_f32_e32 v135, v135
	v_or_b32_e32 v132, s9, v170
	v_ashrrev_i32_e32 v132, 1, v132
	v_add_u32_e32 v134, s8, v172
	v_add_f32_e32 v135, 1.0, v135
	s_movk_i32 s8, 0x1600
	v_mfma_f32_32x32x16_bf16 v[100:115], v[218:221], v[148:151], v[100:115]
	v_mfma_f32_32x32x16_bf16 v[52:67], v[186:189], v[140:143], v[52:67]
	v_mfma_f32_32x32x16_bf16 v[36:51], v[178:181], v[140:143], v[36:51]
	v_rcp_f32_e32 v140, v135
	v_mul_f32_e32 v135, 0xbfb8aa3b, v117
	v_exp_f32_e32 v135, v135
	s_nop 0
	v_add_f32_e32 v135, 1.0, v135
	v_mfma_f32_32x32x16_bf16 v[100:115], v[178:181], v[152:155], v[100:115]
	v_rcp_f32_e32 v141, v135
	s_nop 0
	v_pk_mul_f32 v[116:117], v[116:117], v[140:141]
	v_mfma_f32_32x32x16_bf16 v[20:35], v[186:189], v[136:139], v[20:35]
	s_nop 7
	v_mul_f32_e64 v100, v100, v116
	v_mul_f32_e64 v101, v101, v117
	v_mul_f32_e32 v116, 0xbfb8aa3b, v118
	v_mul_f32_e32 v117, 0xbfb8aa3b, v119
	v_exp_f32_e32 v116, v116
	v_exp_f32_e32 v117, v117
	v_add_f32_e32 v116, 1.0, v116
	v_add_f32_e32 v117, 1.0, v117
	v_rcp_f32_e32 v116, v116
	v_rcp_f32_e32 v117, v117
	v_mfma_f32_32x32x16_bf16 v[4:19], v[178:181], v[136:139], v[4:19]
	v_or_b32_e32 v136, v132, v171
	v_mov_b64_e32 v[132:133], s[2:3]
	v_mul_f32_e64 v116, v118, v116
; DI unsigned pack2(float a, float b) { f2_t v = {a, b}; return __builtin_bit_cast(unsigned, __builtin_convertvector(v, bf2_t)); }
; DI float siluf(float x) { return x * __builtin_amdgcn_rcpf(1.f + __expf(-x)); }
;   template <int MF> DI void operator()(f32x16 (&acc)[MF][2], int mb, int nb, int l31, int h) const {
; #pragma unroll
;     for (int mi = 0; mi < MF; ++mi) {
;       const int row = mb + mi * 32 + l31;
; #pragma unroll
;       for (int gp = 0; gp < 2; ++gp) {
;         const int j0 = (nb >> 1) + 16 * h + 8 * gp;
;         float v[8];
; #pragma unroll
;         for (int i = 0; i < 8; ++i) v[i] = siluf(acc[mi][0][8 * gp + i]) * acc[mi][1][8 * gp + i];
;         *(u32x4*)(act + (size_t)row * FF + j0) = (u32x4){pack2(v[0], v[1]), pack2(v[2], v[3]), pack2(v[4], v[5]), pack2(v[6], v[7])};
;       }
;     }
;   }
	v_mul_f32_e64 v117, v119, v117
	v_ashrrev_i32_e32 v137, 31, v136
	v_pk_mul_f32 v[116:117], v[102:103], v[116:117]
	v_mul_f32_e32 v102, 0xbfb8aa3b, v120
	v_mul_f32_e32 v103, 0xbfb8aa3b, v121
	v_exp_f32_e32 v102, v102
	v_exp_f32_e32 v103, v103
	v_mad_i64_i32 v[138:139], s[4:5], v134, s8, v[132:133]
	v_add_f32_e32 v102, 1.0, v102
	v_add_f32_e32 v103, 1.0, v103
	v_rcp_f32_e32 v102, v102
	v_rcp_f32_e32 v103, v103
	v_mfma_f32_32x32x16_bf16 v[84:99], v[182:185], v[204:207], v[84:99]
	v_mul_f32_e64 v102, v120, v102
	v_mul_f32_e64 v103, v121, v103
	v_mul_f32_e64 v104, v104, v102
	v_mul_f32_e64 v105, v105, v103
	v_mul_f32_e32 v102, 0xbfb8aa3b, v122
	v_mul_f32_e32 v103, 0xbfb8aa3b, v123
	v_exp_f32_e32 v102, v102
	v_exp_f32_e32 v103, v103
	v_cvt_pk_bf16_f32 v104, v104, v105
	v_mfma_f32_32x32x16_bf16 v[84:99], v[186:189], v[144:147], v[84:99]
	v_add_f32_e32 v102, 1.0, v102
	v_add_f32_e32 v103, 1.0, v103
	v_rcp_f32_e32 v102, v102
	v_rcp_f32_e32 v103, v103
	s_nop 0
	v_pk_mul_f32 v[102:103], v[122:123], v[102:103]
	s_nop 0
	v_pk_mul_f32 v[106:107], v[106:107], v[102:103]
	v_cvt_pk_bf16_f32 v102, v100, v101
	v_lshlrev_b64 v[100:101], 1, v[136:137]
	v_cvt_pk_bf16_f32 v103, v116, v117
	v_cvt_pk_bf16_f32 v105, v106, v107
	v_lshl_add_u64 v[106:107], v[138:139], 0, v[100:101]
	global_store_dwordx4 v[106:107], v[102:105], off
	v_mfma_f32_32x32x16_bf16 v[68:83], v[218:221], v[204:207], v[68:83]
	s_nop 0
	v_mul_f32_e32 v102, 0xbfb8aa3b, v124
	v_mul_f32_e32 v103, 0xbfb8aa3b, v125
	v_mul_f32_e32 v104, 0xbfb8aa3b, v126
	v_mul_f32_e32 v105, 0xbfb8aa3b, v127
	v_exp_f32_e32 v102, v102
	v_exp_f32_e32 v103, v103
	v_exp_f32_e32 v104, v104
	v_exp_f32_e32 v105, v105
	v_add_f32_e32 v102, 1.0, v102
	v_add_f32_e32 v103, 1.0, v103
	v_add_f32_e32 v104, 1.0, v104
	v_add_f32_e32 v105, 1.0, v105
	v_rcp_f32_e32 v102, v102
	v_rcp_f32_e32 v103, v103
	v_rcp_f32_e32 v104, v104
	v_rcp_f32_e32 v105, v105
	v_mfma_f32_32x32x16_bf16 v[68:83], v[178:181], v[144:147], v[68:83]
	v_mul_f32_e64 v102, v124, v102
	v_mul_f32_e64 v103, v125, v103
	v_mul_f32_e64 v104, v126, v104
	v_mul_f32_e64 v105, v127, v105
	v_mul_f32_e64 v102, v108, v102
	v_mul_f32_e64 v103, v109, v103
	v_pk_mul_f32 v[104:105], v[110:111], v[104:105]
	v_mul_f32_e32 v108, 0xbfb8aa3b, v128
	v_mul_f32_e32 v109, 0xbfb8aa3b, v129
	v_mul_f32_e32 v110, 0xbfb8aa3b, v130
	v_mul_f32_e32 v111, 0xbfb8aa3b, v131
	v_exp_f32_e32 v108, v108
	v_exp_f32_e32 v109, v109
	v_exp_f32_e32 v110, v110
	v_exp_f32_e32 v111, v111
	v_add_f32_e32 v108, 1.0, v108
	v_add_f32_e32 v109, 1.0, v109
	v_add_f32_e32 v110, 1.0, v110
	v_add_f32_e32 v111, 1.0, v111
	v_rcp_f32_e32 v108, v108
	v_rcp_f32_e32 v109, v109
	v_rcp_f32_e32 v110, v110
	v_rcp_f32_e32 v111, v111
	v_cvt_pk_bf16_f32 v102, v102, v103
	v_pk_mul_f32 v[108:109], v[128:129], v[108:109]
	v_cvt_pk_bf16_f32 v103, v104, v105
	v_pk_mul_f32 v[110:111], v[130:131], v[110:111]
	v_pk_mul_f32 v[108:109], v[112:113], v[108:109]
	v_pk_mul_f32 v[110:111], v[114:115], v[110:111]
	v_cvt_pk_bf16_f32 v104, v108, v109
	v_cvt_pk_bf16_f32 v105, v110, v111
	global_store_dwordx4 v[106:107], v[102:105], off offset:16
	s_nop 1
	v_mul_f32_e32 v104, 0xbfb8aa3b, v84
	v_mul_f32_e32 v105, 0xbfb8aa3b, v85
	v_exp_f32_e32 v104, v104
	v_exp_f32_e32 v105, v105
	v_or_b32_e32 v102, 32, v134
	v_mad_i64_i32 v[102:103], s[4:5], v102, s8, v[132:133]
	v_add_f32_e32 v104, 1.0, v104
	v_add_f32_e32 v105, 1.0, v105
	v_rcp_f32_e32 v104, v104
	v_rcp_f32_e32 v105, v105
	s_nop 0
	v_pk_mul_f32 v[84:85], v[84:85], v[104:105]
	s_nop 0
	v_pk_mul_f32 v[68:69], v[68:69], v[84:85]
	v_mul_f32_e32 v84, 0xbfb8aa3b, v86
	v_mul_f32_e32 v85, 0xbfb8aa3b, v87
	v_exp_f32_e32 v84, v84
	v_exp_f32_e32 v85, v85
	v_cvt_pk_bf16_f32 v68, v68, v69
	v_add_f32_e32 v84, 1.0, v84
	v_add_f32_e32 v85, 1.0, v85
	v_rcp_f32_e32 v84, v84
	v_rcp_f32_e32 v85, v85
	s_nop 0
	v_pk_mul_f32 v[84:85], v[86:87], v[84:85]
	s_nop 0
	v_pk_mul_f32 v[70:71], v[70:71], v[84:85]
	v_mul_f32_e32 v84, 0xbfb8aa3b, v88
	v_mul_f32_e32 v85, 0xbfb8aa3b, v89
	v_exp_f32_e32 v84, v84
	v_exp_f32_e32 v85, v85
	v_cvt_pk_bf16_f32 v69, v70, v71
	v_add_f32_e32 v84, 1.0, v84
	v_add_f32_e32 v85, 1.0, v85
	v_rcp_f32_e32 v84, v84
	v_rcp_f32_e32 v85, v85
	s_nop 0
	v_pk_mul_f32 v[84:85], v[88:89], v[84:85]
	s_nop 0
	v_pk_mul_f32 v[72:73], v[72:73], v[84:85]
	v_mul_f32_e32 v84, 0xbfb8aa3b, v90
	v_mul_f32_e32 v85, 0xbfb8aa3b, v91
	v_exp_f32_e32 v84, v84
	v_exp_f32_e32 v85, v85
	v_cvt_pk_bf16_f32 v70, v72, v73
	v_lshl_add_u64 v[72:73], v[102:103], 0, v[100:101]
	v_add_f32_e32 v84, 1.0, v84
	v_add_f32_e32 v85, 1.0, v85
	v_rcp_f32_e32 v84, v84
	v_rcp_f32_e32 v85, v85
	s_nop 0
	v_pk_mul_f32 v[84:85], v[90:91], v[84:85]
	s_nop 0
	v_pk_mul_f32 v[74:75], v[74:75], v[84:85]
	s_nop 0
	v_cvt_pk_bf16_f32 v71, v74, v75
	global_store_dwordx4 v[72:73], v[68:71], off
	v_mul_f32_e32 v74, 0xbfb8aa3b, v96
	v_mul_f32_e32 v75, 0xbfb8aa3b, v97
	v_mul_f32_e32 v68, 0xbfb8aa3b, v92
	v_mul_f32_e32 v69, 0xbfb8aa3b, v93
	v_exp_f32_e32 v68, v68
	v_exp_f32_e32 v69, v69
	v_mul_f32_e32 v70, 0xbfb8aa3b, v94
	v_mul_f32_e32 v71, 0xbfb8aa3b, v95
	v_add_f32_e32 v68, 1.0, v68
	v_add_f32_e32 v69, 1.0, v69
	v_rcp_f32_e32 v68, v68
	v_rcp_f32_e32 v69, v69
	v_exp_f32_e32 v70, v70
	v_exp_f32_e32 v71, v71
	v_exp_f32_e32 v74, v74
	v_pk_mul_f32 v[68:69], v[92:93], v[68:69]
	v_exp_f32_e32 v75, v75
	v_pk_mul_f32 v[68:69], v[76:77], v[68:69]
	v_mul_f32_e32 v76, 0xbfb8aa3b, v98
	v_mul_f32_e32 v77, 0xbfb8aa3b, v99
	v_exp_f32_e32 v76, v76
	v_exp_f32_e32 v77, v77
	v_add_f32_e32 v70, 1.0, v70
	v_add_f32_e32 v71, 1.0, v71
	v_add_f32_e32 v74, 1.0, v74
	v_add_f32_e32 v75, 1.0, v75
	v_add_f32_e32 v76, 1.0, v76
	v_add_f32_e32 v77, 1.0, v77
	v_rcp_f32_e32 v70, v70
	v_rcp_f32_e32 v71, v71
; DI int bid_l() { int t = blockIdx.x; asm volatile("" : "+s"(t)); return t; }
; DI unsigned pack2(float a, float b) { f2_t v = {a, b}; return __builtin_bit_cast(unsigned, __builtin_convertvector(v, bf2_t)); }
; DI float siluf(float x) { return x * __builtin_amdgcn_rcpf(1.f + __expf(-x)); }
; template <int MF, int BK, class Epi>
; DI void gemm_phase_t(char* lds, const GemmDesc g, const Epi epi) {
;     ...
;   for (int t = bid_l(); t < ntiles; t += gridDim.x) {
;   template <int MF> DI void operator()(f32x16 (&acc)[MF][2], int mb, int nb, int l31, int h) const {
; #pragma unroll
;     for (int mi = 0; mi < MF; ++mi) {
;       const int row = mb + mi * 32 + l31;
; #pragma unroll
;       for (int gp = 0; gp < 2; ++gp) {
;         const int j0 = (nb >> 1) + 16 * h + 8 * gp;
;         float v[8];
; #pragma unroll
;         for (int i = 0; i < 8; ++i) v[i] = siluf(acc[mi][0][8 * gp + i]) * acc[mi][1][8 * gp + i];
;         *(u32x4*)(act + (size_t)row * FF + j0) = (u32x4){pack2(v[0], v[1]), pack2(v[2], v[3]), pack2(v[4], v[5]), pack2(v[6], v[7])};
;       }
;     }
;   }
	v_rcp_f32_e32 v74, v74
	v_rcp_f32_e32 v75, v75
	v_rcp_f32_e32 v76, v76
	v_rcp_f32_e32 v77, v77
	v_pk_mul_f32 v[70:71], v[94:95], v[70:71]
	v_pk_mul_f32 v[74:75], v[96:97], v[74:75]
	v_pk_mul_f32 v[70:71], v[78:79], v[70:71]
	v_pk_mul_f32 v[76:77], v[98:99], v[76:77]
	v_pk_mul_f32 v[74:75], v[80:81], v[74:75]
	v_pk_mul_f32 v[76:77], v[82:83], v[76:77]
	v_cvt_pk_bf16_f32 v68, v68, v69
	v_cvt_pk_bf16_f32 v69, v70, v71
	v_cvt_pk_bf16_f32 v70, v74, v75
	v_cvt_pk_bf16_f32 v71, v76, v77
	global_store_dwordx4 v[72:73], v[68:71], off offset:16
	s_nop 1
	v_mul_f32_e32 v70, 0xbfb8aa3b, v52
	v_mul_f32_e32 v71, 0xbfb8aa3b, v53
	v_exp_f32_e32 v70, v70
	v_exp_f32_e32 v71, v71
	v_or_b32_e32 v68, 64, v134
	v_mad_i64_i32 v[68:69], s[4:5], v68, s8, v[132:133]
	v_add_f32_e32 v70, 1.0, v70
	v_add_f32_e32 v71, 1.0, v71
	v_rcp_f32_e32 v70, v70
	v_rcp_f32_e32 v71, v71
	s_nop 0
	v_pk_mul_f32 v[52:53], v[52:53], v[70:71]
	s_nop 0
	v_pk_mul_f32 v[36:37], v[36:37], v[52:53]
	v_mul_f32_e32 v52, 0xbfb8aa3b, v54
	v_mul_f32_e32 v53, 0xbfb8aa3b, v55
	v_exp_f32_e32 v52, v52
	v_exp_f32_e32 v53, v53
	v_cvt_pk_bf16_f32 v36, v36, v37
	v_add_f32_e32 v52, 1.0, v52
	v_add_f32_e32 v53, 1.0, v53
	v_rcp_f32_e32 v52, v52
	v_rcp_f32_e32 v53, v53
	s_nop 0
	v_pk_mul_f32 v[52:53], v[54:55], v[52:53]
	s_nop 0
	v_pk_mul_f32 v[38:39], v[38:39], v[52:53]
	v_mul_f32_e32 v52, 0xbfb8aa3b, v56
	v_mul_f32_e32 v53, 0xbfb8aa3b, v57
	v_exp_f32_e32 v52, v52
	v_exp_f32_e32 v53, v53
	v_cvt_pk_bf16_f32 v37, v38, v39
	v_add_f32_e32 v52, 1.0, v52
	v_add_f32_e32 v53, 1.0, v53
	v_rcp_f32_e32 v52, v52
	v_rcp_f32_e32 v53, v53
	s_nop 0
	v_pk_mul_f32 v[52:53], v[56:57], v[52:53]
	s_nop 0
	v_pk_mul_f32 v[40:41], v[40:41], v[52:53]
	v_mul_f32_e32 v52, 0xbfb8aa3b, v58
	v_mul_f32_e32 v53, 0xbfb8aa3b, v59
	v_exp_f32_e32 v52, v52
	v_exp_f32_e32 v53, v53
	v_cvt_pk_bf16_f32 v38, v40, v41
	v_lshl_add_u64 v[40:41], v[68:69], 0, v[100:101]
	v_add_f32_e32 v52, 1.0, v52
	v_add_f32_e32 v53, 1.0, v53
	v_rcp_f32_e32 v52, v52
	v_rcp_f32_e32 v53, v53
	s_nop 0
	v_pk_mul_f32 v[52:53], v[58:59], v[52:53]
	s_nop 0
	v_pk_mul_f32 v[42:43], v[42:43], v[52:53]
	s_nop 0
	v_cvt_pk_bf16_f32 v39, v42, v43
	global_store_dwordx4 v[40:41], v[36:39], off
	v_mul_f32_e32 v42, 0xbfb8aa3b, v64
	v_mul_f32_e32 v43, 0xbfb8aa3b, v65
	v_mul_f32_e32 v36, 0xbfb8aa3b, v60
	v_mul_f32_e32 v37, 0xbfb8aa3b, v61
	v_exp_f32_e32 v36, v36
	v_exp_f32_e32 v37, v37
	v_mul_f32_e32 v38, 0xbfb8aa3b, v62
	v_mul_f32_e32 v39, 0xbfb8aa3b, v63
	v_add_f32_e32 v36, 1.0, v36
	v_add_f32_e32 v37, 1.0, v37
	v_rcp_f32_e32 v36, v36
	v_rcp_f32_e32 v37, v37
	v_exp_f32_e32 v38, v38
	v_exp_f32_e32 v39, v39
	v_exp_f32_e32 v42, v42
	v_pk_mul_f32 v[36:37], v[60:61], v[36:37]
	v_exp_f32_e32 v43, v43
	v_pk_mul_f32 v[36:37], v[44:45], v[36:37]
	v_mul_f32_e32 v44, 0xbfb8aa3b, v66
	v_mul_f32_e32 v45, 0xbfb8aa3b, v67
	v_exp_f32_e32 v44, v44
	v_exp_f32_e32 v45, v45
	v_add_f32_e32 v38, 1.0, v38
	v_add_f32_e32 v39, 1.0, v39
	v_add_f32_e32 v42, 1.0, v42
	v_add_f32_e32 v43, 1.0, v43
	v_add_f32_e32 v44, 1.0, v44
	v_add_f32_e32 v45, 1.0, v45
	v_rcp_f32_e32 v38, v38
	v_rcp_f32_e32 v39, v39
	v_rcp_f32_e32 v42, v42
	v_rcp_f32_e32 v43, v43
	v_rcp_f32_e32 v44, v44
	v_rcp_f32_e32 v45, v45
	v_pk_mul_f32 v[38:39], v[62:63], v[38:39]
	v_pk_mul_f32 v[42:43], v[64:65], v[42:43]
	v_pk_mul_f32 v[38:39], v[46:47], v[38:39]
	v_pk_mul_f32 v[44:45], v[66:67], v[44:45]
	v_pk_mul_f32 v[42:43], v[48:49], v[42:43]
	v_pk_mul_f32 v[44:45], v[50:51], v[44:45]
	v_cvt_pk_bf16_f32 v36, v36, v37
	v_cvt_pk_bf16_f32 v37, v38, v39
	v_cvt_pk_bf16_f32 v38, v42, v43
	v_cvt_pk_bf16_f32 v39, v44, v45
	global_store_dwordx4 v[40:41], v[36:39], off offset:16
	s_nop 1
	v_mul_f32_e32 v38, 0xbfb8aa3b, v20
	v_mul_f32_e32 v39, 0xbfb8aa3b, v21
	v_exp_f32_e32 v38, v38
	v_exp_f32_e32 v39, v39
	v_or_b32_e32 v36, 0x60, v134
	v_mad_i64_i32 v[36:37], s[4:5], v36, s8, v[132:133]
	v_add_f32_e32 v38, 1.0, v38
	v_add_f32_e32 v39, 1.0, v39
	v_rcp_f32_e32 v38, v38
	v_rcp_f32_e32 v39, v39
	v_readlane_b32 s4, v252, 40
	s_add_i32 s7, s7, s4
	s_cmp_ge_i32 s7, s6
	v_pk_mul_f32 v[20:21], v[20:21], v[38:39]
	v_readlane_b32 s5, v252, 41
	v_pk_mul_f32 v[4:5], v[4:5], v[20:21]
	v_mul_f32_e32 v20, 0xbfb8aa3b, v22
	v_mul_f32_e32 v21, 0xbfb8aa3b, v23
	v_exp_f32_e32 v20, v20
	v_exp_f32_e32 v21, v21
	v_cvt_pk_bf16_f32 v4, v4, v5
	v_add_f32_e32 v20, 1.0, v20
	v_add_f32_e32 v21, 1.0, v21
	v_rcp_f32_e32 v20, v20
	v_rcp_f32_e32 v21, v21
	s_nop 0
	v_pk_mul_f32 v[20:21], v[22:23], v[20:21]
	s_nop 0
	v_pk_mul_f32 v[6:7], v[6:7], v[20:21]
	v_mul_f32_e32 v20, 0xbfb8aa3b, v24
	v_mul_f32_e32 v21, 0xbfb8aa3b, v25
	v_exp_f32_e32 v20, v20
	v_exp_f32_e32 v21, v21
	v_cvt_pk_bf16_f32 v5, v6, v7
	v_add_f32_e32 v20, 1.0, v20
	v_add_f32_e32 v21, 1.0, v21
	v_rcp_f32_e32 v20, v20
	v_rcp_f32_e32 v21, v21
	s_nop 0
	v_pk_mul_f32 v[20:21], v[24:25], v[20:21]
	s_nop 0
	v_pk_mul_f32 v[8:9], v[8:9], v[20:21]
	v_mul_f32_e32 v20, 0xbfb8aa3b, v26
	v_mul_f32_e32 v21, 0xbfb8aa3b, v27
	v_exp_f32_e32 v20, v20
	v_exp_f32_e32 v21, v21
	v_cvt_pk_bf16_f32 v6, v8, v9
	v_lshl_add_u64 v[8:9], v[36:37], 0, v[100:101]
	v_add_f32_e32 v20, 1.0, v20
	v_add_f32_e32 v21, 1.0, v21
	v_rcp_f32_e32 v20, v20
	v_rcp_f32_e32 v21, v21
	s_nop 0
	v_pk_mul_f32 v[20:21], v[26:27], v[20:21]
	s_nop 0
	v_pk_mul_f32 v[10:11], v[10:11], v[20:21]
	s_nop 0
	v_cvt_pk_bf16_f32 v7, v10, v11
	global_store_dwordx4 v[8:9], v[4:7], off
	v_mul_f32_e32 v10, 0xbfb8aa3b, v32
	v_mul_f32_e32 v11, 0xbfb8aa3b, v33
	v_mul_f32_e32 v4, 0xbfb8aa3b, v28
	v_mul_f32_e32 v5, 0xbfb8aa3b, v29
	v_exp_f32_e32 v4, v4
	v_exp_f32_e32 v5, v5
	v_mul_f32_e32 v6, 0xbfb8aa3b, v30
	v_mul_f32_e32 v7, 0xbfb8aa3b, v31
	v_add_f32_e32 v4, 1.0, v4
	v_add_f32_e32 v5, 1.0, v5
	v_rcp_f32_e32 v4, v4
	v_rcp_f32_e32 v5, v5
	v_exp_f32_e32 v6, v6
	v_exp_f32_e32 v7, v7
	v_exp_f32_e32 v10, v10
	v_pk_mul_f32 v[4:5], v[28:29], v[4:5]
	v_exp_f32_e32 v11, v11
	v_pk_mul_f32 v[4:5], v[12:13], v[4:5]
	v_mul_f32_e32 v12, 0xbfb8aa3b, v34
	v_mul_f32_e32 v13, 0xbfb8aa3b, v35
	v_exp_f32_e32 v12, v12
	v_exp_f32_e32 v13, v13
	v_add_f32_e32 v6, 1.0, v6
	v_add_f32_e32 v7, 1.0, v7
	v_add_f32_e32 v10, 1.0, v10
	v_add_f32_e32 v11, 1.0, v11
	v_add_f32_e32 v12, 1.0, v12
	v_add_f32_e32 v13, 1.0, v13
	v_rcp_f32_e32 v6, v6
	v_rcp_f32_e32 v7, v7
	v_rcp_f32_e32 v10, v10
	v_rcp_f32_e32 v11, v11
	v_rcp_f32_e32 v12, v12
	v_rcp_f32_e32 v13, v13
	v_pk_mul_f32 v[6:7], v[30:31], v[6:7]
	v_pk_mul_f32 v[10:11], v[32:33], v[10:11]
	v_pk_mul_f32 v[6:7], v[14:15], v[6:7]
	v_pk_mul_f32 v[12:13], v[34:35], v[12:13]
	v_pk_mul_f32 v[10:11], v[16:17], v[10:11]
	v_pk_mul_f32 v[12:13], v[18:19], v[12:13]
	v_cvt_pk_bf16_f32 v4, v4, v5
	v_cvt_pk_bf16_f32 v5, v6, v7
	v_cvt_pk_bf16_f32 v6, v10, v11
	v_cvt_pk_bf16_f32 v7, v12, v13
	global_store_dwordx4 v[8:9], v[4:7], off offset:16
	s_cbranch_scc0 .LBB0_287

; __global__ void __launch_bounds__(256, 2) mega(Params p) {
;   __shared__ __attribute__((aligned(16))) char lds[LDS_BYTES];
	.amdhsa_kernel _Z4mega6Params
		.amdhsa_group_segment_fixed_size 77840
		.amdhsa_private_segment_fixed_size 0
		.amdhsa_kernarg_size 544
		.amdhsa_user_sgpr_count 2
		.amdhsa_user_sgpr_dispatch_ptr 0
		.amdhsa_user_sgpr_queue_ptr 0
		.amdhsa_user_sgpr_kernarg_segment_ptr 1
		.amdhsa_user_sgpr_dispatch_id 0
		.amdhsa_user_sgpr_kernarg_preload_length 0
		.amdhsa_user_sgpr_kernarg_preload_offset 0
		.amdhsa_user_sgpr_private_segment_size 0
		.amdhsa_uses_dynamic_stack 0
		.amdhsa_enable_private_segment 0
		.amdhsa_system_sgpr_workgroup_id_x 1
		.amdhsa_system_sgpr_workgroup_id_y 0
		.amdhsa_system_sgpr_workgroup_id_z 0
		.amdhsa_system_sgpr_workgroup_info 0
		.amdhsa_system_vgpr_workitem_id 0
		.amdhsa_next_free_vgpr 256
		.amdhsa_next_free_sgpr 102
		.amdhsa_accum_offset 256
		.amdhsa_reserve_vcc 1
		.amdhsa_float_round_mode_32 0
		.amdhsa_float_round_mode_16_64 0
		.amdhsa_float_denorm_mode_32 3
		.amdhsa_float_denorm_mode_16_64 3
		.amdhsa_dx10_clamp 1
		.amdhsa_ieee_mode 1
		.amdhsa_fp16_overflow 0
		.amdhsa_tg_split 0
		.amdhsa_exception_fp_ieee_invalid_op 0
		.amdhsa_exception_fp_denorm_src 0
		.amdhsa_exception_fp_ieee_div_zero 0
		.amdhsa_exception_fp_ieee_overflow 0
		.amdhsa_exception_fp_ieee_underflow 0
		.amdhsa_exception_fp_ieee_inexact 0
		.amdhsa_exception_int_div_zero 0
	.end_amdhsa_kernel

; __global__ void __launch_bounds__(256, 2) mega(Params p) {
;   __shared__ __attribute__((aligned(16))) char lds[LDS_BYTES];
amdhsa.kernels:
  - .agpr_count:     0
    .args:
      - .offset:         0
        .size:           288
        .value_kind:     by_value
      - .offset:         288
        .size:           4
        .value_kind:     hidden_block_count_x
      - .offset:         292
        .size:           4
        .value_kind:     hidden_block_count_y
      - .offset:         296
        .size:           4
        .value_kind:     hidden_block_count_z
      - .offset:         300
        .size:           2
        .value_kind:     hidden_group_size_x
      - .offset:         302
        .size:           2
        .value_kind:     hidden_group_size_y
      - .offset:         304
        .size:           2
        .value_kind:     hidden_group_size_z
      - .offset:         306
        .size:           2
        .value_kind:     hidden_remainder_x
      - .offset:         308
        .size:           2
        .value_kind:     hidden_remainder_y
      - .offset:         310
        .size:           2
        .value_kind:     hidden_remainder_z
      - .offset:         328
        .size:           8
        .value_kind:     hidden_global_offset_x
      - .offset:         336
        .size:           8
        .value_kind:     hidden_global_offset_y
      - .offset:         344
        .size:           8
        .value_kind:     hidden_global_offset_z
      - .offset:         352
        .size:           2
        .value_kind:     hidden_grid_dims
    .group_segment_fixed_size: 77840
    .kernarg_segment_align: 8
    .kernarg_segment_size: 544
    .language:       OpenCL C
    .language_version:
      - 2
      - 0
    .max_flat_workgroup_size: 256
    .name:           _Z4mega6Params
    .private_segment_fixed_size: 0
    .sgpr_count:     108
    .sgpr_spill_count: 366
    .symbol:         _Z4mega6Params.kd
    .uniform_work_group_size: 1
    .uses_dynamic_stack: false
    .vgpr_count:     256
    .vgpr_spill_count: 0
    .wavefront_size: 64
